# attention work queue: ticket for the next item is fetched (global atomic) while the current item runs instead of a blocking round trip per item
# baseline (speedup 1.0000x reference)
; __device__ __forceinline__ void attn_item(const Params& p, unsigned char* lds, int item) {
;     const int tid = threadIdx.x, lane = tid & 63, wave = tid >> 6;
;     const int n = item >> 5, bh = item & 31, h = bh & 7, b = bh >> 3;
;     unsigned char* dob = (unsigned char*)p.out;
;     const bf16_t* proj = (const bf16_t*)(p.ws + WS_PROJ);
;     const bf16_t* mq = proj + 4 * SEC; const bf16_t* mk = proj + 5 * SEC;
;     {
;         const unsigned char* ksrc = (const unsigned char*)(mk + ((size_t)b * NT + n * 256) * 1024 + h * 128);
;         const unsigned char* vsrc = p.ws + WS_T2 + (size_t)((bh * 32) + n) * 65536;
;         int tido = tid; asm volatile("" : "+v"(tido));
; #pragma unroll
;         for (int k = 0; k < 8; ++k) { const int pc = tido + 512 * k, row = pc >> 4, cc = pc & 15;
;             *(u32x4*)(lds + AT_K + row * 272 + cc * 16) = *(const u32x4*)(ksrc + (size_t)row * 2048 + cc * 16); }
; #pragma unroll
;         for (int k = 0; k < 8; ++k) { const int pc = tido + 512 * k, row = pc >> 5, cc = pc & 31;
;             *(u32x4*)(lds + AT_V + row * 528 + cc * 16) = *(const u32x4*)(vsrc + (size_t)pc * 16); }
;         *(u32x4*)(lds + AT_B + tido * 16) = *(const u32x4*)((const unsigned char*)dob + DO_BIAS + (size_t)h * 32768 + tido * 16);
;     }
;     __syncthreads();
;     volatile unsigned* queue = (volatile unsigned*)(lds + AT_Q) + wave * 128;
;     const unsigned* sel = (const unsigned*)(dob + DO_SEL) + (size_t)bh * NT;
;     float* ML = (float*)(dob + DO_ML);
;     bf16_t* projw = (bf16_t*)(p.ws + WS_PROJ);
;     const int qi = lane & 15, g4 = lane >> 4;
;     const int nchunks = (NT - (n + 1) * 256) / 64;
;     const float* biasL = (const float*)(lds + AT_B);
;     int own_left = 1, cc = wave, count = 0;
;     unsigned svb0, svb1, svb2, svb3; int svn, ccl = wave;
; __global__ void __launch_bounds__(512, 2) fwd_kernel(Params p) {
;     ...
;         volatile int* misc = (volatile int*)(lds + AT_MISC);
;         for (;;) {
;             if (tid == 0) misc[0] = (int)atomicAdd(cnt, 1u);
.Lprio_skip_at:
	s_bitcmp0_b32 s30, 3
	s_cselect_b64 s[44:45], -1, 0
	s_add_u32 s46, s34, 0x1c000000
	s_addc_u32 s47, s35, 0
	s_add_u32 s50, s34, 0x3c000000
	s_addc_u32 s51, s35, 0
	s_add_u32 s52, s34, 0x18000000
	s_addc_u32 s53, s35, 0
	s_add_u32 s54, s26, 0xeb80000
	s_addc_u32 s55, s27, 0
	s_add_i32 s3, 0, 0x21800
	s_add_u32 s68, s26, 0xea00000
	s_addc_u32 s69, s27, 0
	s_mov_b64 s[42:43], src_shared_base
	s_add_u32 s70, s26, 0xe200000
	v_and_b32_e32 v194, 15, v220
	v_mov_b32_e32 v1, 0
	v_and_b32_e32 v0, 48, v222
	s_waitcnt vmcnt(0)
	v_lshlrev_b64 v[4:5], v222, -1
	s_addc_u32 s71, s27, 0
	v_lshl_add_u64 v[148:149], s[52:53], 0, v[0:1]
	v_not_b32_e32 v151, v5
	v_and_b32_e32 v0, 48, v220
	v_mul_u32_u24_e32 v5, 0x210, v194
	s_add_i32 s42, 0, 0x11000
	v_lshrrev_b32_e32 v3, 4, v222
	v_add3_u32 v205, s42, v5, v0
	v_not_b32_e32 v5, 31
	v_mad_i32_i24 v207, v3, -4, v5
	v_not_b32_e32 v5, 63
	v_mad_i32_i24 v208, v3, -4, v5
	v_mov_b32_e32 v5, 0xffffffa0
	v_mad_i32_i24 v209, v3, -4, v5
	v_mov_b32_e32 v5, 0xffffff80
	v_mad_i32_i24 v210, v3, -4, v5
	v_mov_b32_e32 v5, 0xffffff60
	v_lshl_add_u32 v161, v223, 9, s3
	v_not_b32_e32 v150, v4
	v_add_u32_e32 v4, 0, v0
	v_mul_u32_u24_e32 v0, 0x110, v194
	v_mad_i32_i24 v211, v3, -4, v5
	v_mov_b32_e32 v5, 0xffffff40
	v_lshlrev_b32_e32 v2, 3, v3
	v_lshl_add_u32 v152, v194, 2, v161
	v_lshl_add_u32 v156, v222, 2, v161
	s_movk_i32 s90, 0x110
	v_mad_i32_i24 v212, v3, -4, v5
	v_mov_b32_e32 v5, 0xffffff20
	v_add_u32_e32 v214, v4, v0
	v_mbcnt_lo_u32_b32 v0, -1, 0
	v_cmp_eq_u32_e64 s[0:1], 0, v220
	v_and_b32_e32 v195, 0x3c0, v220
	v_add_u32_e32 v196, 8, v223
	v_or_b32_e32 v197, 16, v223
	v_add_u32_e32 v198, 24, v223
	v_lshl_or_b32 v199, v223, 5, v194
	v_or_b32_e32 v200, 32, v223
	v_lshl_add_u32 v201, v223, 1, 2
	v_mov_b32_e32 v153, s43
	v_or_b32_e32 v202, 16, v194
	v_add_u32_e32 v154, 64, v152
	v_mov_b32_e32 v155, s43
	v_add_u32_e32 v203, 32, v222
	v_add_u32_e32 v158, 0x80, v156
	v_mov_b32_e32 v159, s43
	v_mov_b32_e32 v157, s43
	v_mul_i32_i24_e32 v204, -4, v3
	s_movk_i32 s3, 0x210
	v_lshlrev_b32_e32 v160, 2, v3
	v_cmp_gt_u32_e64 s[4:5], 16, v222
	v_mad_u32_u24 v206, v194, s90, v4
	v_mad_i32_i24 v213, v3, -4, v5
	s_mov_b64 s[72:73], 0
	s_add_i32 s91, 0, 0x24800
	s_movk_i32 s92, 0x400
	v_lshlrev_b32_e32 v162, 1, v2
	s_movk_i32 s93, 0x5e8
	s_add_i32 s94, 0, 0x247fc
	s_mov_b32 s95, 0xf149f2ca
	v_mbcnt_hi_u32_b32 v215, -1, v0
	v_mov_b32_e32 v216, 0xffff0000
	v_mov_b32_e32 v217, 0x20000
	v_mov_b32_e32 v218, 0x10000
	v_mov_b32_e32 v219, 0xf149f2ca
	s_and_saveexec_b64 s[6:7], s[0:1]
	v_mov_b32_e32 v252, 1
	global_atomic_add v252, v1, v252, s[40:41] sc0
	s_or_b64 exec, exec, s[6:7]
	s_branch .LBB0_312

; #define AT_REFILL() do { const unsigned so = (unsigned)((n + 1) * 256 + lane + 64 * ccl);        \
;         svb0 = (ccl < nchunks) ? sel[so] : 0xFFFFFFFFu; svb1 = (ccl + 8 < nchunks) ? sel[so + 512u] : 0xFFFFFFFFu; \
;         svb2 = (ccl + 16 < nchunks) ? sel[so + 1024u] : 0xFFFFFFFFu; svb3 = (ccl + 24 < nchunks) ? sel[so + 1536u] : 0xFFFFFFFFu; ccl += 32; svn = 4; } while (0)
; __device__ __forceinline__ void attn_item(const Params& p, unsigned char* lds, int item) {
;     ...
;     {
;         const unsigned char* ksrc = (const unsigned char*)(mk + ((size_t)b * NT + n * 256) * 1024 + h * 128);
;         const unsigned char* vsrc = p.ws + WS_T2 + (size_t)((bh * 32) + n) * 65536;
;         int tido = tid; asm volatile("" : "+v"(tido));
; #pragma unroll
;         for (int k = 0; k < 8; ++k) { const int pc = tido + 512 * k, row = pc >> 4, cc = pc & 15;
;             *(u32x4*)(lds + AT_K + row * 272 + cc * 16) = *(const u32x4*)(ksrc + (size_t)row * 2048 + cc * 16); }
; #pragma unroll
;         for (int k = 0; k < 8; ++k) { const int pc = tido + 512 * k, row = pc >> 5, cc = pc & 31;
;             *(u32x4*)(lds + AT_V + row * 528 + cc * 16) = *(const u32x4*)(vsrc + (size_t)pc * 16); }
;         *(u32x4*)(lds + AT_B + tido * 16) = *(const u32x4*)((const unsigned char*)dob + DO_BIAS + (size_t)h * 32768 + tido * 16);
;     }
;     __syncthreads();
;     volatile unsigned* queue = (volatile unsigned*)(lds + AT_Q) + wave * 128;
;     const unsigned* sel = (const unsigned*)(dob + DO_SEL) + (size_t)bh * NT;
;     float* ML = (float*)(dob + DO_ML);
;     bf16_t* projw = (bf16_t*)(p.ws + WS_PROJ);
;     const int qi = lane & 15, g4 = lane >> 4;
;     const int nchunks = (NT - (n + 1) * 256) / 64;
;     const float* biasL = (const float*)(lds + AT_B);
;     int own_left = 1, cc = wave, count = 0;
;     unsigned svb0, svb1, svb2, svb3; int svn, ccl = wave;
;     ...
;     AT_REFILL();
; __global__ void __launch_bounds__(512, 2) fwd_kernel(Params p) {
;     ...
;         for (;;) {
;             if (tid == 0) misc[0] = (int)atomicAdd(cnt, 1u);
;             __syncthreads();
;             const int it = misc[0];
;             __syncthreads();
;             if (it >= 1024 || (p.flags & 8)) break;
.LBB0_312:
	s_and_saveexec_b64 s[6:7], s[0:1]
	s_cbranch_execz .LBB0_316
	s_waitcnt vmcnt(0)
	v_mov_b32_e32 v0, v252
	s_cmp_lg_u32 s91, -1
	s_cselect_b32 s9, s43, 0
	s_cselect_b32 s8, s91, 0
	v_mov_b32_e32 v2, s8
	v_mov_b32_e32 v3, s9
	flat_store_dword v[2:3], v0 sc0 sc1
	s_waitcnt vmcnt(0)
.LBB0_316:
	s_or_b64 exec, exec, s[6:7]
	s_cmp_lg_u32 s91, -1
	s_cselect_b32 s6, s91, 0
	s_cselect_b32 s7, s43, 0
	v_mov_b32_e32 v2, s6
	v_mov_b32_e32 v3, s7
	s_waitcnt lgkmcnt(0)
	s_barrier
	flat_load_dword v0, v[2:3] sc0 sc1
	s_waitcnt vmcnt(0)
	s_mov_b64 s[6:7], -1
	s_waitcnt lgkmcnt(0)
	s_barrier
	s_and_saveexec_b64 s[8:9], s[0:1]
	v_mov_b32_e32 v252, 1
	global_atomic_add v252, v1, v252, s[40:41] sc0
	s_or_b64 exec, exec, s[8:9]
	v_cmp_gt_i32_e32 vcc, s92, v0
	s_and_b64 s[8:9], vcc, s[44:45]
	s_and_saveexec_b64 s[74:75], s[8:9]
	s_cbranch_execz .LBB0_311
	v_ashrrev_i32_e32 v221, 5, v0
	v_and_b32_e32 v2, 31, v0
	v_and_b32_e32 v3, 7, v0
	v_lshlrev_b32_e32 v0, 10, v0
	v_lshlrev_b32_e32 v166, 8, v221
	v_and_b32_e32 v164, 0x6000, v0
	v_mov_b32_e32 v165, v1
	v_ashrrev_i32_e32 v167, 31, v166
	v_lshl_add_u64 v[4:5], v[164:165], 0, v[166:167]
	v_mov_b32_e32 v72, v220
	v_lshlrev_b64 v[4:5], 11, v[4:5]
	v_lshl_add_u64 v[4:5], s[46:47], 0, v[4:5]
	v_add_u32_e32 v78, 0x200, v72
	v_lshlrev_b32_e32 v0, 8, v3
	v_lshlrev_b32_e32 v74, 4, v72
	v_ashrrev_i32_e32 v76, 4, v72
	v_ashrrev_i32_e32 v80, 4, v78
	v_lshl_add_u64 v[4:5], v[4:5], 0, v[0:1]
	v_and_b32_e32 v0, 0xf0, v74
	v_ashrrev_i32_e32 v77, 31, v76
	v_ashrrev_i32_e32 v81, 31, v80
	v_add_u32_e32 v82, 0x400, v72
	v_add_u32_e32 v86, 0x600, v72
	v_lshl_add_u64 v[32:33], v[4:5], 0, v[0:1]
	v_lshlrev_b64 v[4:5], 11, v[76:77]
	v_lshlrev_b64 v[6:7], 11, v[80:81]
	v_ashrrev_i32_e32 v84, 4, v82
	v_ashrrev_i32_e32 v88, 4, v86
	v_lshl_add_u64 v[4:5], v[32:33], 0, v[4:5]
	v_lshl_add_u64 v[8:9], v[32:33], 0, v[6:7]
	v_ashrrev_i32_e32 v85, 31, v84
	v_ashrrev_i32_e32 v89, 31, v88
	v_add_u32_e32 v90, 0x800, v72
	v_add_u32_e32 v94, 0xa00, v72
	global_load_dwordx4 v[4:7], v[4:5], off
	s_nop 0
	global_load_dwordx4 v[8:11], v[8:9], off
	v_lshlrev_b64 v[12:13], 11, v[84:85]
	v_lshlrev_b64 v[14:15], 11, v[88:89]
	v_ashrrev_i32_e32 v92, 4, v90
	v_ashrrev_i32_e32 v96, 4, v94
	v_add_u32_e32 v98, 0xc00, v72
	v_lshl_add_u64 v[12:13], v[32:33], 0, v[12:13]
	v_lshl_add_u64 v[16:17], v[32:33], 0, v[14:15]
	v_ashrrev_i32_e32 v93, 31, v92
	v_ashrrev_i32_e32 v97, 31, v96
	v_ashrrev_i32_e32 v100, 4, v98
	v_add_u32_e32 v102, 0xe00, v72
	global_load_dwordx4 v[12:15], v[12:13], off
	s_nop 0
	global_load_dwordx4 v[16:19], v[16:17], off
	v_lshlrev_b64 v[20:21], 11, v[92:93]
	v_lshlrev_b64 v[22:23], 11, v[96:97]
	v_ashrrev_i32_e32 v101, 31, v100
	v_ashrrev_i32_e32 v104, 4, v102
	v_lshl_add_u32 v36, v2, 5, v221
	v_lshl_add_u64 v[20:21], v[32:33], 0, v[20:21]
	v_lshl_add_u64 v[24:25], v[32:33], 0, v[22:23]
	v_lshlrev_b64 v[28:29], 11, v[100:101]
	v_ashrrev_i32_e32 v105, 31, v104
	global_load_dwordx4 v[20:23], v[20:21], off
	s_nop 0
	global_load_dwordx4 v[24:27], v[24:25], off
	v_lshl_add_u64 v[28:29], v[32:33], 0, v[28:29]
	v_lshlrev_b64 v[34:35], 11, v[104:105]
	v_ashrrev_i32_e32 v37, 31, v36
	global_load_dwordx4 v[28:31], v[28:29], off
	v_lshl_add_u64 v[32:33], v[32:33], 0, v[34:35]
	v_lshlrev_b64 v[36:37], 16, v[36:37]
	global_load_dwordx4 v[32:35], v[32:33], off
	v_lshl_add_u64 v[64:65], s[50:51], 0, v[36:37]
	v_ashrrev_i32_e32 v73, 31, v72
	v_lshl_add_u64 v[36:37], v[72:73], 4, v[64:65]
	global_load_dwordx4 v[36:39], v[36:37], off
	v_ashrrev_i32_e32 v79, 31, v78
	v_lshl_add_u64 v[40:41], v[78:79], 4, v[64:65]
	global_load_dwordx4 v[40:43], v[40:41], off
	v_ashrrev_i32_e32 v83, 31, v82
	v_lshl_add_u64 v[44:45], v[82:83], 4, v[64:65]
	global_load_dwordx4 v[44:47], v[44:45], off
	v_ashrrev_i32_e32 v87, 31, v86
	v_lshl_add_u64 v[48:49], v[86:87], 4, v[64:65]
	global_load_dwordx4 v[48:51], v[48:49], off
	v_ashrrev_i32_e32 v91, 31, v90
	v_lshl_add_u64 v[52:53], v[90:91], 4, v[64:65]
	global_load_dwordx4 v[52:55], v[52:53], off
	v_ashrrev_i32_e32 v95, 31, v94
	v_lshl_add_u64 v[56:57], v[94:95], 4, v[64:65]
	global_load_dwordx4 v[56:59], v[56:57], off
	v_ashrrev_i32_e32 v99, 31, v98
	v_lshl_add_u64 v[60:61], v[98:99], 4, v[64:65]
	v_add_u32_e32 v106, 0, v0
	global_load_dwordx4 v[60:63], v[60:61], off
	v_lshlrev_b32_e32 v0, 15, v3
	v_ashrrev_i32_e32 v103, 31, v102
	v_lshl_add_u64 v[68:69], s[54:55], 0, v[0:1]
	v_ashrrev_i32_e32 v75, 31, v74
	v_lshl_add_u64 v[64:65], v[102:103], 4, v[64:65]
	v_lshl_add_u64 v[68:69], v[68:69], 0, v[74:75]
	global_load_dwordx4 v[64:67], v[64:65], off
	v_mad_u64_u32 v[76:77], s[6:7], v76, s90, v[106:107]
	global_load_dwordx4 v[68:71], v[68:69], off
	v_and_b32_e32 v0, 0x1f0, v74
	v_add_u32_e32 v0, s42, v0
	v_add_u32_e32 v167, 0x100, v166
	v_or_b32_e32 v225, v167, v222
	v_mov_b32_e32 v227, -1
	v_mov_b32_e32 v226, -1
	s_waitcnt vmcnt(16)
	ds_write_b128 v76, v[4:7]
	v_mad_u64_u32 v[4:5], s[6:7], v80, s90, v[106:107]
	s_waitcnt vmcnt(15)
	ds_write_b128 v4, v[8:11]
	v_mad_u64_u32 v[4:5], s[6:7], v84, s90, v[106:107]
	s_waitcnt vmcnt(14)
	ds_write_b128 v4, v[12:15]
	v_mad_u64_u32 v[4:5], s[6:7], v88, s90, v[106:107]
	s_waitcnt vmcnt(13)
	ds_write_b128 v4, v[16:19]
	v_mad_u64_u32 v[4:5], s[6:7], v92, s90, v[106:107]
	s_waitcnt vmcnt(12)
	ds_write_b128 v4, v[20:23]
	v_mad_u64_u32 v[4:5], s[6:7], v96, s90, v[106:107]
	s_waitcnt vmcnt(11)
	ds_write_b128 v4, v[24:27]
	v_mad_u64_u32 v[4:5], s[6:7], v100, s90, v[106:107]
	s_waitcnt vmcnt(10)
	ds_write_b128 v4, v[28:31]
	v_mad_u64_u32 v[4:5], s[6:7], v104, s90, v[106:107]
	s_waitcnt vmcnt(9)
	ds_write_b128 v4, v[32:35]
	v_ashrrev_i32_e32 v4, 5, v72
	v_mad_u64_u32 v[4:5], s[6:7], v4, s3, v[0:1]
	s_waitcnt vmcnt(8)
	ds_write_b128 v4, v[36:39]
	v_ashrrev_i32_e32 v4, 5, v78
	v_mad_u64_u32 v[4:5], s[6:7], v4, s3, v[0:1]
	s_waitcnt vmcnt(7)
	ds_write_b128 v4, v[40:43]
	v_ashrrev_i32_e32 v4, 5, v82
	v_mad_u64_u32 v[4:5], s[6:7], v4, s3, v[0:1]
	s_waitcnt vmcnt(6)
	ds_write_b128 v4, v[44:47]
	v_ashrrev_i32_e32 v4, 5, v86
	v_mad_u64_u32 v[4:5], s[6:7], v4, s3, v[0:1]
	s_waitcnt vmcnt(5)
	ds_write_b128 v4, v[48:51]
	v_ashrrev_i32_e32 v4, 5, v90
	v_mad_u64_u32 v[4:5], s[6:7], v4, s3, v[0:1]
	s_waitcnt vmcnt(4)
	ds_write_b128 v4, v[52:55]
	v_ashrrev_i32_e32 v4, 5, v94
	v_mad_u64_u32 v[4:5], s[6:7], v4, s3, v[0:1]
	s_waitcnt vmcnt(3)
	ds_write_b128 v4, v[56:59]
	v_ashrrev_i32_e32 v4, 5, v98
	v_mad_u64_u32 v[4:5], s[6:7], v4, s3, v[0:1]
	s_waitcnt vmcnt(2)
	ds_write_b128 v4, v[60:63]
	v_ashrrev_i32_e32 v4, 5, v102
	v_mad_u64_u32 v[4:5], s[6:7], v4, s3, v[0:1]
	v_add_u32_e32 v0, 0, v74
	v_add_u32_e32 v0, 0x22800, v0
	s_waitcnt vmcnt(1)
	ds_write_b128 v4, v[64:67]
	s_waitcnt vmcnt(0)
	ds_write_b128 v0, v[68:71]
	v_lshlrev_b32_e32 v0, 15, v2
	v_lshl_add_u64 v[168:169], s[68:69], 0, v[0:1]
	v_sub_u32_e32 v0, 0x1f00, v166
	v_lshrrev_b32_e32 v224, 6, v0
	v_add_u32_e32 v0, v225, v195
	v_cmp_lt_u32_e32 vcc, v223, v224
	s_waitcnt lgkmcnt(0)
	s_barrier
	s_and_saveexec_b64 s[6:7], vcc
	s_cbranch_execz .LBB0_319
	v_lshl_add_u64 v[4:5], v[0:1], 2, v[168:169]
	global_load_dword v226, v[4:5], off
